# dilated work queues: chunks of 4 consecutive units per grab (whole tile-sharing pairs stay in one wave, 25 % fewer queue round trips)
# baseline (speedup 1.0000x reference)
.LBB0_493:
	s_or_b64 exec, exec, s[82:83]
	v_readfirstlane_b32 s14, v0
	s_cmpk_gt_u32 s14, 0x8ff
	s_mov_b64 s[82:83], -1
	s_cbranch_scc1 .LBB0_488
	s_mul_i32 s14, s14, 4
	s_add_i32 s8, s14, s60
	s_lshr_b32 s33, s8, 8
	s_mul_i32 s34, s33, 0xaaab
	s_lshr_b32 s34, s34, 17
	s_mul_i32 s34, s34, 3
	s_sub_i32 s33, s33, s34
	s_and_b32 s83, s33, 0xffff
	s_lshl_b32 s62, s83, 1
	s_lshr_b32 s34, 0x100, s62
	s_and_b32 s15, s14, 0xff
	s_sub_i32 s33, 8, s62
	s_add_i32 s34, s34, -1
	s_mul_hi_u32 s8, s8, 0xaaaaaaab
	s_lshr_b32 s33, s15, s33
	s_and_b32 s15, s34, s15
	s_bfe_u32 s82, s8, 0x30009
	s_lshl_b32 s15, s15, 5
	s_lshl_b32 s8, s8, 1
	s_and_b32 s48, s8, 0x3e000
	v_or_b32_e32 v184, s15, v162
	v_mov_b32_e32 v185, v167
	v_lshlrev_b64 v[0:1], s62, v[184:185]
	s_or_b32 s8, s33, s48
	s_add_i32 s34, s82, 1
	v_lshlrev_b32_e32 v2, s62, v168
	v_lshl_add_u64 v[182:183], v[0:1], 0, s[8:9]
	v_cvt_f32_ubyte0_e32 v0, s34
	s_lshl_b32 s34, 1, s62
	v_add_u32_e32 v2, s8, v2
	v_mov_b32_e32 v3, v167
	s_and_b32 s92, s15, 0x1fc0
	v_exp_f32_e64 v12, -v0
	v_cvt_f32_u32_e32 v13, s34
	v_lshlrev_b64 v[0:1], 12, v[182:183]
	s_lshl_b32 s34, s82, 7
	v_lshlrev_b64 v[2:3], 12, v[2:3]
	v_lshl_add_u64 v[0:1], s[22:23], 0, v[0:1]
	s_mov_b32 s35, s9
	v_lshl_add_u64 v[2:3], s[22:23], 0, v[2:3]
	s_cmp_eq_u32 s83, 1
	v_lshl_add_u64 v[0:1], v[0:1], 0, s[34:35]
	v_lshl_add_u64 v[2:3], v[2:3], 0, s[34:35]
	s_cselect_b32 s8, s20, s26
	s_cselect_b32 s34, s21, s27
	s_cmp_eq_u32 s83, 0
	s_cselect_b32 s34, s54, s34
	s_cselect_b32 s8, s49, s8
	v_lshl_or_b32 v8, s82, 6, v164
	v_mov_b32_e32 v6, s8
	v_mov_b32_e32 v7, s34
	v_mul_i32_i24_e32 v8, 0x18000, v8
	v_mov_b32_e32 v9, v167
	v_lshl_add_u64 v[6:7], v[8:9], 1, v[6:7]
	s_lshl_b32 s8, s48, 1
	v_lshl_add_u64 v[6:7], v[6:7], 0, s[8:9]
	s_sub_i32 s8, 13, s62
	s_lshl_b32 s8, s33, s8
	s_mov_b32 s93, s9
	s_lshl_b32 s8, s8, 1
	s_lshl_b64 s[34:35], s[92:93], s62
	v_lshl_add_u64 v[4:5], v[2:3], 0, v[178:179]
	v_lshl_add_u64 v[6:7], v[6:7], 0, s[8:9]
	s_lshl_b64 s[34:35], s[34:35], 12
	v_lshl_add_u64 v[52:53], v[6:7], 0, v[178:179]
	v_lshl_add_u64 v[54:55], v[6:7], 0, v[180:181]
	v_lshl_add_u64 v[6:7], v[4:5], 0, s[34:35]
	s_or_b32 s34, s92, 4
	s_mov_b32 s35, s9
	s_lshl_b64 s[34:35], s[34:35], s62
	v_lshl_add_u64 v[2:3], v[2:3], 0, v[180:181]
	s_lshl_b64 s[34:35], s[34:35], 12
	s_lshl_b32 s8, s92, 1
	v_lshl_add_u64 v[8:9], v[2:3], 0, s[34:35]
	global_load_dwordx4 v[64:67], v[6:7], off offset:3072
	global_load_dwordx4 v[72:75], v[8:9], off offset:3072
	v_lshl_add_u64 v[6:7], v[52:53], 0, s[8:9]
	v_lshl_add_u64 v[8:9], v[54:55], 0, s[8:9]
	s_or_b32 s8, s92, 16
	v_add_co_u32_e32 v10, vcc, s1, v8
	s_lshl_b64 s[34:35], s[8:9], s62
	s_nop 0
	v_addc_co_u32_e32 v11, vcc, 0, v9, vcc
	s_lshl_b64 s[34:35], s[34:35], 12
	global_load_dwordx4 v[76:79], v[10:11], off
	v_lshl_add_u64 v[10:11], v[4:5], 0, s[34:35]
	s_or_b32 s8, s92, 20
	global_load_dwordx4 v[80:83], v[10:11], off offset:3072
	v_add_co_u32_e32 v10, vcc, s52, v6
	s_lshl_b64 s[34:35], s[8:9], s62
	s_nop 0
	v_addc_co_u32_e32 v11, vcc, 0, v7, vcc
	s_lshl_b64 s[34:35], s[34:35], 12
	global_load_dwordx4 v[84:87], v[10:11], off
	v_lshl_add_u64 v[10:11], v[2:3], 0, s[34:35]
	s_or_b32 s8, s15, 32
	global_load_dwordx4 v[88:91], v[10:11], off offset:3072
	v_add_co_u32_e32 v10, vcc, s53, v8
	s_lshl_b64 s[34:35], s[8:9], s62
	s_nop 0
	v_addc_co_u32_e32 v11, vcc, 0, v9, vcc
	s_lshl_b64 s[34:35], s[34:35], 12
	global_load_dwordx4 v[92:95], v[10:11], off
	v_lshl_add_u64 v[10:11], v[4:5], 0, s[34:35]
	s_or_b32 s8, s15, 36
	global_load_dwordx4 v[96:99], v[10:11], off offset:3072
	v_add_co_u32_e32 v10, vcc, s6, v6
	s_lshl_b64 s[34:35], s[8:9], s62
	s_nop 0
	v_addc_co_u32_e32 v11, vcc, 0, v7, vcc
	s_lshl_b64 s[34:35], s[34:35], 12
	s_or_b32 s8, s15, 48
	global_load_dwordx4 v[100:103], v[10:11], off
	v_lshl_add_u64 v[10:11], v[2:3], 0, s[34:35]
	s_lshl_b64 s[34:35], s[8:9], s62
	global_load_dwordx4 v[104:107], v[10:11], off offset:3072
	v_add_co_u32_e32 v10, vcc, s7, v8
	s_lshl_b64 s[34:35], s[34:35], 12
	s_or_b32 s8, s15, 52
	v_lshl_add_u64 v[50:51], v[4:5], 0, s[10:11]
	v_addc_co_u32_e32 v11, vcc, 0, v9, vcc
	v_lshl_add_u64 v[4:5], v[4:5], 0, s[34:35]
	s_lshl_b64 s[34:35], s[8:9], s62
	global_load_dwordx4 v[112:115], v[4:5], off offset:3072
	v_add_co_u32_e32 v4, vcc, s42, v6
	s_lshl_b64 s[34:35], s[34:35], 12
	v_lshl_add_u64 v[48:49], v[2:3], 0, s[10:11]
	v_addc_co_u32_e32 v5, vcc, 0, v7, vcc
	v_lshl_add_u64 v[2:3], v[2:3], 0, s[34:35]
	global_load_dwordx4 v[120:123], v[2:3], off offset:3072
	v_add_co_u32_e32 v2, vcc, 0xa80000, v8
	v_mov_b32_e32 v177, v167
	s_nop 0
	v_addc_co_u32_e32 v3, vcc, 0, v9, vcc
	v_lshl_add_u64 v[0:1], v[0:1], 0, v[176:177]
	global_load_dwordx4 v[68:71], v[6:7], off
	global_load_dwordx4 v[116:119], v[4:5], off
	global_load_dwordx4 v[108:111], v[10:11], off
	global_load_dwordx4 v[140:143], v[2:3], off
	global_load_dwordx4 v[136:139], v[0:1], off offset:2048
	global_load_dwordx4 v[132:135], v[0:1], off offset:2080
	global_load_dwordx4 v[128:131], v[0:1], off offset:2112
	global_load_dwordx4 v[124:127], v[0:1], off offset:2144
	v_mul_f32_e32 v0, 0x3fb8aa3b, v12
	s_mov_b32 s63, 0
	s_lshr_b32 s34, 0x2000, s62
	v_mul_f32_e32 v186, v0, v13
	s_add_i32 s14, s61, s14
	s_branch .LBB0_496
.LBB0_495:
	s_or_b64 exec, exec, s[84:85]
	s_add_i32 s63, s63, 1
	s_cmp_eq_u32 s63, 4
	v_mov_b64_e32 v[182:183], v[190:191]
	s_mov_b32 s62, s95
	s_mov_b32 s83, s93
	s_mov_b32 s82, s56
	s_cbranch_scc1 .LBB0_487
.LBB0_496:
	s_cmp_lg_u32 s63, 3
	s_cselect_b64 s[86:87], -1, 0
	s_cmp_gt_i32 s92, 63
	s_cselect_b64 s[96:97], -1, 0
	s_add_i32 s84, s92, 64
	s_cmp_lt_i32 s84, s34
	s_cselect_b64 s[88:89], -1, 0
	s_cmp_ge_i32 s84, s34
	s_cselect_b64 s[90:91], -1, 0
	s_cmp_lt_i32 s92, 64
	s_waitcnt vmcnt(19)
	ds_write_b128 v222, v[64:67]
	s_waitcnt vmcnt(7)
	ds_write_b128 v222, v[68:71] offset:8192
	ds_write_b128 v222, v[72:75] offset:1024
	ds_write_b128 v222, v[76:79] offset:9216
	ds_write_b128 v222, v[80:83] offset:2048
	ds_write_b128 v222, v[84:87] offset:10240
	ds_write_b128 v222, v[88:91] offset:3072
	ds_write_b128 v222, v[92:95] offset:11264
	ds_write_b128 v222, v[96:99] offset:4096
	ds_write_b128 v222, v[100:103] offset:12288
	ds_write_b128 v222, v[104:107] offset:5120
	s_waitcnt vmcnt(5)
	ds_write_b128 v222, v[108:111] offset:13312
	ds_write_b128 v222, v[112:115] offset:6144
	ds_write_b128 v222, v[116:119] offset:14336
	ds_write_b128 v222, v[120:123] offset:7168
	s_waitcnt vmcnt(4)
	ds_write_b128 v222, v[140:143] offset:15360
	s_cbranch_scc0 .LBB0_501
	s_and_b64 vcc, exec, s[90:91]
	s_cbranch_vccz .LBB0_502
	s_waitcnt vmcnt(0)
	v_mov_b64_e32 v[32:33], v[124:125]
	v_mov_b64_e32 v[36:37], v[128:129]
	v_mov_b64_e32 v[40:41], v[132:133]
	v_mov_b64_e32 v[44:45], v[136:137]
	s_andn2_b64 vcc, exec, s[86:87]
	v_mov_b64_e32 v[60:61], v[50:51]
	v_mov_b64_e32 v[62:63], v[48:49]
	v_mov_b64_e32 v[200:201], v[52:53]
	v_mov_b64_e32 v[202:203], v[54:55]
	v_mov_b64_e32 v[56:57], v[182:183]
	v_mov_b32_e32 v59, v186
	s_mov_b32 s94, s92
	s_mov_b32 s15, s62
	s_mov_b32 s48, s34
	v_mov_b32_e32 v58, v184
	s_mov_b32 s35, s83
	s_mov_b32 s33, s82
	v_mov_b64_e32 v[34:35], v[126:127]
	v_mov_b64_e32 v[38:39], v[130:131]
	v_mov_b64_e32 v[42:43], v[134:135]
	v_mov_b64_e32 v[46:47], v[138:139]
	s_cbranch_vccnz .LBB0_500
	s_add_i32 s8, s14, s63
	s_lshr_b32 s15, s8, 8
	s_mul_hi_u32 s33, s15, 0x55555556
	s_mul_i32 s33, s33, 3
	s_sub_i32 s35, s15, s33
	s_lshl_b32 s15, s35, 1
	s_lshr_b32 s85, 0x100, s15
	s_and_b32 s48, s8, 0xff
	s_sub_i32 s56, 8, s15
	s_add_i32 s85, s85, -1
	s_mul_hi_u32 s8, s8, 0xaaaaaaab
	s_lshr_b32 s56, s48, s56
	s_and_b32 s48, s85, s48
	s_bfe_u32 s33, s8, 0x30009
	s_lshl_b32 s48, s48, 5
	s_lshl_b32 s8, s8, 1
	s_and_b32 s85, s8, 0xfe000
	v_or_b32_e32 v58, s48, v162
	v_mov_b32_e32 v59, v167
	v_lshlrev_b64 v[0:1], s15, v[58:59]
	s_or_b32 s8, s56, s85
	s_add_i32 s93, s33, 1
	s_and_b32 s94, s48, 0x1fc0
	v_lshl_add_u64 v[56:57], v[0:1], 0, s[8:9]
	v_cvt_f32_ubyte0_e32 v0, s93
	s_lshl_b32 s93, 1, s15
	s_lshl_b32 vcc_lo, s33, 7
	v_lshlrev_b32_e32 v2, s15, v168
	s_cmp_eq_u32 s35, 1
	v_cvt_f32_u32_e32 v13, s93
	v_add_u32_e32 v2, s8, v2
	s_cselect_b32 s8, s20, s26
	s_cselect_b32 s93, s21, s27
	s_cmp_eq_u32 s35, 0
	s_cselect_b32 s93, s54, s93
	s_cselect_b32 s8, s49, s8
	v_lshl_or_b32 v8, s33, 6, v164
	v_mov_b32_e32 v6, s8
	v_mov_b32_e32 v7, s93
	v_mul_i32_i24_e32 v8, 0x18000, v8
	v_mov_b32_e32 v9, v167
	v_mov_b32_e32 v3, v167
	v_lshl_add_u64 v[6:7], v[8:9], 1, v[6:7]
	s_lshl_b32 s8, s85, 1
	v_exp_f32_e64 v12, -v0
	v_lshlrev_b64 v[0:1], 12, v[56:57]
	v_lshlrev_b64 v[2:3], 12, v[2:3]
	v_lshl_add_u64 v[6:7], v[6:7], 0, s[8:9]
	s_sub_i32 s8, 13, s15
	v_lshl_add_u64 v[0:1], s[22:23], 0, v[0:1]
	s_mov_b32 vcc_hi, s9
	v_lshl_add_u64 v[2:3], s[22:23], 0, v[2:3]
	s_lshl_b32 s8, s56, s8
	s_mov_b32 s95, s9
	v_lshl_add_u64 v[0:1], v[0:1], 0, vcc
	v_lshl_add_u64 v[2:3], v[2:3], 0, vcc
	s_lshl_b32 s8, s8, 1
	s_lshl_b64 vcc, s[94:95], s15
	v_lshl_add_u64 v[4:5], v[2:3], 0, v[178:179]
	v_lshl_add_u64 v[6:7], v[6:7], 0, s[8:9]
	s_lshl_b64 vcc, vcc, 12
	v_lshl_add_u64 v[200:201], v[6:7], 0, v[178:179]
	v_lshl_add_u64 v[202:203], v[6:7], 0, v[180:181]
	v_lshl_add_u64 v[6:7], v[4:5], 0, vcc
	s_or_b32 vcc_lo, s94, 4
	s_mov_b32 vcc_hi, s9
	s_lshl_b64 vcc, vcc, s15
	v_lshl_add_u64 v[2:3], v[2:3], 0, v[180:181]
	s_lshl_b64 vcc, vcc, 12
	s_lshl_b32 s8, s94, 1
	v_lshl_add_u64 v[8:9], v[2:3], 0, vcc
	global_load_dwordx4 v[64:67], v[6:7], off offset:3072
	global_load_dwordx4 v[72:75], v[8:9], off offset:3072
	v_lshl_add_u64 v[8:9], v[202:203], 0, s[8:9]
	v_add_co_u32_e32 v10, vcc, s1, v8
	v_lshl_add_u64 v[6:7], v[200:201], 0, s[8:9]
	s_nop 0
	v_addc_co_u32_e32 v11, vcc, 0, v9, vcc
	s_or_b32 s8, s94, 16
	s_lshl_b64 vcc, s[8:9], s15
	s_lshl_b64 vcc, vcc, 12
	global_load_dwordx4 v[76:79], v[10:11], off
	v_lshl_add_u64 v[10:11], v[4:5], 0, vcc
	global_load_dwordx4 v[80:83], v[10:11], off offset:3072
	v_add_co_u32_e32 v10, vcc, s52, v6
	s_or_b32 s8, s94, 20
	s_nop 0
	v_addc_co_u32_e32 v11, vcc, 0, v7, vcc
	s_lshl_b64 vcc, s[8:9], s15
	s_lshl_b64 vcc, vcc, 12
	global_load_dwordx4 v[84:87], v[10:11], off
	v_lshl_add_u64 v[10:11], v[2:3], 0, vcc
	global_load_dwordx4 v[88:91], v[10:11], off offset:3072
	v_add_co_u32_e32 v10, vcc, s53, v8
	s_or_b32 s8, s48, 32
	s_nop 0
	v_addc_co_u32_e32 v11, vcc, 0, v9, vcc
	s_lshl_b64 vcc, s[8:9], s15
	s_lshl_b64 vcc, vcc, 12
	global_load_dwordx4 v[92:95], v[10:11], off
	v_lshl_add_u64 v[10:11], v[4:5], 0, vcc
	global_load_dwordx4 v[96:99], v[10:11], off offset:3072
	v_add_co_u32_e32 v10, vcc, s6, v6
	s_or_b32 s8, s48, 36
	s_nop 0
	v_addc_co_u32_e32 v11, vcc, 0, v7, vcc
	s_lshl_b64 vcc, s[8:9], s15
	s_lshl_b64 vcc, vcc, 12
	global_load_dwordx4 v[100:103], v[10:11], off
	v_lshl_add_u64 v[10:11], v[2:3], 0, vcc
	global_load_dwordx4 v[104:107], v[10:11], off offset:3072
	v_add_co_u32_e32 v10, vcc, s7, v8
	s_or_b32 s8, s48, 48
	s_nop 0
	v_addc_co_u32_e32 v11, vcc, 0, v9, vcc
	s_lshl_b64 vcc, s[8:9], s15
	s_lshl_b64 vcc, vcc, 12
	v_lshl_add_u64 v[60:61], v[4:5], 0, s[10:11]
	v_lshl_add_u64 v[4:5], v[4:5], 0, vcc
	global_load_dwordx4 v[112:115], v[4:5], off offset:3072
	v_add_co_u32_e32 v4, vcc, s42, v6
	s_or_b32 s8, s48, 52
	s_nop 0
	v_addc_co_u32_e32 v5, vcc, 0, v7, vcc
	s_lshl_b64 vcc, s[8:9], s15
	s_lshl_b64 vcc, vcc, 12
	v_lshl_add_u64 v[62:63], v[2:3], 0, s[10:11]
	v_lshl_add_u64 v[2:3], v[2:3], 0, vcc
	global_load_dwordx4 v[120:123], v[2:3], off offset:3072
	v_add_co_u32_e32 v2, vcc, 0xa80000, v8
	v_mov_b32_e32 v177, v167
	s_nop 0
	v_addc_co_u32_e32 v3, vcc, 0, v9, vcc
	v_lshl_add_u64 v[0:1], v[0:1], 0, v[176:177]
	global_load_dwordx4 v[68:71], v[6:7], off
	global_load_dwordx4 v[116:119], v[4:5], off
	global_load_dwordx4 v[108:111], v[10:11], off
	global_load_dwordx4 v[140:143], v[2:3], off
	global_load_dwordx4 v[44:47], v[0:1], off offset:2048
	global_load_dwordx4 v[40:43], v[0:1], off offset:2080
	global_load_dwordx4 v[36:39], v[0:1], off offset:2112
	global_load_dwordx4 v[32:35], v[0:1], off offset:2144
	v_mul_f32_e32 v0, 0x3fb8aa3b, v12
	s_lshr_b32 s48, 0x2000, s15
	v_mul_f32_e32 v59, v0, v13
